# attention: cheap (edge-clipped) latent items remapped onto the workgroups that also carry a context-query item
# baseline (speedup 1.0000x reference)
.LBB0_296:
	s_mov_b32 s43, s100
	s_add_i32 s43, s43, s28
	s_cmp_lt_i32 s43, s23
	s_barrier
	s_cbranch_scc0 .LBB0_384
.LBB0_297:
	s_mov_b32 s100, s43
	s_cmp_ge_i32 s43, s22
	s_mov_b64 s[34:35], -1
	s_cbranch_scc0 .LBB0_305
	s_sub_i32 s3, s43, s22
	s_sext_i32_i16 s0, s3
	s_mulk_i32 s0, 0xe39
	s_lshr_b32 s1, s0, 31
	s_lshr_b32 s2, s0, 16
	s_add_i32 s2, s2, s1
	s_mul_i32 s19, s2, 18
	v_mov_b32_e32 v0, v188
	s_sub_i32 s3, s3, s19
	s_sext_i32_i16 s3, s3
	v_and_b32_e32 v2, 15, v0
	v_lshl_or_b32 v3, s3, 4, v2
	s_mov_b32 s3, 0x38e38e39
	v_mul_hi_i32 v4, v3, s3
	v_lshrrev_b32_e32 v5, 31, v4
	v_ashrrev_i32_e32 v4, 3, v4
	v_add_u32_e32 v11, v4, v5
	v_mul_lo_u32 v4, v11, 36
	v_sub_u32_e32 v10, v3, v4
	v_cmp_lt_i32_e32 vcc, 3, v10
	v_lshlrev_b32_e32 v4, 6, v10
	s_and_saveexec_b64 s[26:27], vcc
	s_xor_b64 s[34:35], exec, s[26:27]
	v_lshlrev_b32_e32 v3, 11, v11
	s_movk_i32 s3, 0xff00
	v_add3_u32 v3, v3, v4, s3
	s_andn2_saveexec_b64 s[34:35], s[34:35]
	v_lshlrev_b32_e32 v3, 8, v11
	v_add3_u32 v3, v3, v4, s74
	s_or_b64 exec, exec, s[34:35]
	s_ashr_i32 s0, s0, 17
	s_add_i32 s19, s0, s1
	v_mad_i64_i32 v[4:5], s[0:1], v3, s59, 0
	s_lshl_b32 s0, s19, 4
	v_lshrrev_b32_e32 v6, 4, v0
	s_ashr_i32 s1, s0, 31
	v_and_or_b32 v4, v0, 16, v4
	s_lshl_b32 s3, s19, 1
	v_bfe_u32 v3, v6, 1, 1
	v_ashrrev_i32_e32 v6, 1, v0
	v_lshl_add_u64 v[4:5], s[0:1], 1, v[4:5]
	v_readlane_b32 s0, v253, 10
	s_and_b32 s2, s2, 1
	v_and_b32_e32 v12, 0xffffffe0, v6
	s_add_i32 s0, s0, s3
	v_mul_u32_u24_e32 v3, 0x500, v3
	s_add_i32 s0, s0, s2
	v_or_b32_e32 v2, v12, v2
	v_bfe_u32 v24, v0, 4, 2
	v_lshlrev_b32_e32 v0, 1, v3
	s_ashr_i32 s1, s0, 31
	v_ashrrev_i32_e32 v3, 31, v2
	s_lshl_b64 s[0:1], s[0:1], 18
	v_lshlrev_b64 v[2:3], 11, v[2:3]
	v_lshl_add_u64 v[16:17], s[0:1], 0, v[2:3]
	v_mov_b32_e32 v2, 0
	v_lshl_add_u64 v[14:15], v[4:5], 0, v[0:1]
	v_lshl_or_b32 v16, v24, 4, v16
	s_mov_b32 s19, 32
	v_mov_b32_e32 v3, v2
	v_mov_b32_e32 v4, v2
	v_mov_b32_e32 v5, v2
	v_mov_b32_e32 v6, v2
	v_mov_b32_e32 v7, v2
	v_mov_b32_e32 v8, v2
	v_mov_b32_e32 v9, v2
	v_readlane_b32 s28, v252, 50
	v_readlane_b32 s29, v252, 51

.LBB0_305:
	s_and_b64 vcc, exec, s[34:35]
	s_cbranch_vccz .LBB0_296
	s_cmpk_ge_u32 s43, 0x200
	s_cbranch_scc1 .Lrm_done
	s_cmpk_ge_u32 s43, 0x40
	s_cbranch_scc1 .Lrm_high
	s_and_b32 s0, s43, 3
	s_add_i32 s1, s0, 28
	s_cmp_lt_u32 s0, 2
	s_cselect_b32 s0, s0, s1
	s_lshr_b32 s1, s43, 3
	s_lshl_b32 s1, s1, 6
	s_or_b32 s0, s0, s1
	s_and_b32 s1, s43, 4
	s_lshl_b32 s1, s1, 3
	s_or_b32 s43, s0, s1
	s_branch .Lrm_done
.Lrm_high:
	s_and_b32 s0, s43, 31
	s_add_i32 s1, s0, -2
	s_cmp_lt_u32 s1, 28
	s_cbranch_scc1 .Lrm_done
	s_add_i32 s1, s0, -28
	s_cmp_lt_u32 s0, 2
	s_cselect_b32 s0, s0, s1
	s_lshr_b32 s1, s43, 6
	s_lshl_b32 s1, s1, 3
	s_or_b32 s0, s0, s1
	s_lshr_b32 s1, s43, 3
	s_and_b32 s1, s1, 4
	s_or_b32 s0, s0, s1
	s_add_i32 s0, s0, -8
	s_add_i32 s1, s0, 6
	s_add_i32 s43, s0, 2
	s_cmp_lt_u32 s0, 28
	s_cselect_b32 s43, s43, s1
.Lrm_done:
	s_add_i32 s0, s43, 0xfffffe00
	s_lshr_b32 s2, s0, 3
	s_ashr_i32 s3, s43, 6
	s_cmpk_gt_i32 s43, 0x1ff
	s_cselect_b64 s[0:1], -1, 0
	s_and_b64 s[0:1], s[0:1], exec
	s_cselect_b32 s0, s2, s3
	s_lshl_b32 s44, s0, 8
	s_addk_i32 s44, 0x4000
	s_lshl_b32 s45, s0, 11
	s_cmpk_gt_i32 s43, 0x1ff
	s_cselect_b64 s[0:1], -1, 0
	s_and_b64 vcc, s[0:1], exec
	s_cselect_b32 s0, 2, 5
	v_mov_b32_e32 v4, v188
	s_cselect_b32 s1, 3, 31
	s_cselect_b32 s3, s44, s45
	s_lshr_b32 s2, s43, s0
	s_and_b32 s0, s1, s43
	v_ashrrev_i32_e32 v0, 6, v4
	s_and_b32 s2, s2, 1
	s_lshl_b32 s54, s0, 6
	v_lshl_add_u32 v5, s2, 2, v0
	v_and_b32_e32 v3, 31, v4
	s_add_i32 s3, s3, s54
	v_lshlrev_b32_e32 v6, 6, v5
	v_or_b32_e32 v180, s3, v3
	v_ashrrev_i32_e32 v7, 31, v6
	v_mov_b64_e32 v[8:9], s[20:21]
	v_bfe_u32 v2, v4, 5, 1
	v_mad_i64_i32 v[10:11], s[26:27], v180, s59, v[8:9]
	v_lshlrev_b64 v[176:177], 1, v[6:7]
	v_lshl_add_u64 v[6:7], v[10:11], 0, v[176:177]
	v_lshlrev_b32_e32 v0, 4, v2
	v_lshl_add_u64 v[6:7], v[6:7], 0, v[0:1]
	v_or_b32_e32 v178, 32, v180
	global_load_dwordx4 v[96:99], v[6:7], off offset:1024
	global_load_dwordx4 v[100:103], v[6:7], off offset:1056
	global_load_dwordx4 v[104:107], v[6:7], off offset:1088
	global_load_dwordx4 v[108:111], v[6:7], off offset:1120
	v_mad_i64_i32 v[6:7], s[26:27], v178, s59, v[8:9]
	v_lshl_add_u64 v[6:7], v[6:7], 0, v[176:177]
	v_lshl_add_u64 v[6:7], v[6:7], 0, v[0:1]
	global_load_dwordx4 v[112:115], v[6:7], off offset:1024
	global_load_dwordx4 v[116:119], v[6:7], off offset:1056
	global_load_dwordx4 v[120:123], v[6:7], off offset:1088
	global_load_dwordx4 v[124:127], v[6:7], off offset:1120
	s_mov_b32 s47, 0
	s_mov_b32 s53, 0
	s_mov_b32 s52, 0
	s_cbranch_vccnz .LBB0_308
	s_sub_i32 s1, 0x80, s54
	s_ashr_i32 s1, s1, 5
	s_cmp_lt_u32 s0, 2
	s_cselect_b32 s52, s1, 0
	s_sub_i32 s0, 0x860, s54
	s_lshr_b32 s0, s0, 5
	s_min_u32 s0, s0, 9
	s_sub_i32 s0, s0, s52
	s_add_i32 s53, s0, 1
